# strategy 4 mirror: static s_setprio 1 for waves 0-3 instead, all flips deleted
# baseline (speedup 1.0000x reference)
; #define LAS __attribute__((address_space(3)))
; __global__ void __launch_bounds__(NWAVES * 64, 2) fwd_kernel(Args args) {
;     extern __shared__ __attribute__((aligned(16))) unsigned char lds[];
;     LAS unsigned char* L = (LAS unsigned char*)lds;
;     const int G = gridDim.x, bx = blockIdx.x;
;     for (int u = threadIdx.x; u < (LDS_BYTES - LDSCTL_OFF) / 4; u += NWAVES * 64) ((LAS unsigned*)(L + LDSCTL_OFF))[u] = 0u;
_Z10fwd_kernel4Args:
	v_readfirstlane_b32 s98, v0
	s_nop 3
	s_and_b32 s98, s98, 0x3ff
	s_lshr_b32 s98, s98, 6
	s_cmp_ge_u32 s98, 4
	s_cbranch_scc1 .Lprio_done
	s_setprio 1
